# prologue x->bf16 row loop: counted vmcnt waits (3,2,1,0) placed at the first use of each of the four row loads instead of one vmcnt(0)
# baseline (speedup 1.0000x reference)
.LBB0_200:
	global_load_dwordx4 v[4:7], v[22:23], off offset:-3072
	global_load_dwordx4 v[0:3], v[22:23], off offset:-2048
	global_load_dwordx4 v[8:11], v[22:23], off offset:-1024
	global_load_dwordx4 v[12:15], v[22:23], off
	s_waitcnt vmcnt(3)
	v_mul_f32_e32 v17, v5, v5
	v_mul_f32_e32 v30, v7, v7
	s_waitcnt vmcnt(2)
	v_mul_f32_e32 v31, v1, v1
	v_mul_f32_e32 v33, v3, v3
	s_waitcnt vmcnt(1)
	v_mul_f32_e32 v34, v9, v9
	v_mul_f32_e32 v35, v11, v11
	v_fmac_f32_e32 v17, v4, v4
	v_fmac_f32_e32 v30, v6, v6
	v_fmac_f32_e32 v31, v0, v0
	v_fmac_f32_e32 v33, v2, v2
	s_waitcnt vmcnt(0)
	v_mul_f32_e32 v36, v13, v13
	v_mul_f32_e32 v37, v15, v15
	v_fmac_f32_e32 v34, v8, v8
	v_fmac_f32_e32 v35, v10, v10
	v_add_f32_e32 v17, v17, v30
	v_add_f32_e32 v30, v31, v33
	v_fmac_f32_e32 v36, v12, v12
	v_fmac_f32_e32 v37, v14, v14
	v_add_f32_e32 v31, v34, v35
	v_add_f32_e32 v17, v17, v30
	v_add_f32_e32 v17, v17, v31
	v_add_f32_e32 v30, v36, v37
	v_add_f32_e32 v17, v17, v30
	s_nop 1
	v_add_f32_dpp v17, v17, v17 row_ror:1 row_mask:0xf bank_mask:0xf
	s_nop 1
	v_add_f32_dpp v17, v17, v17 row_ror:2 row_mask:0xf bank_mask:0xf
	s_nop 1
	v_add_f32_dpp v17, v17, v17 row_ror:4 row_mask:0xf bank_mask:0xf
	s_nop 1
	v_add_f32_dpp v17, v17, v17 row_ror:8 row_mask:0xf bank_mask:0xf
	v_mov_b32_e32 v30, v17
	s_nop 1
	v_permlane16_swap_b32 v30, v17
	v_add_f32_e32 v17, v17, v30
	v_mov_b32_e32 v30, v17
	s_nop 1
	v_permlane32_swap_b32 v30, v17
	s_and_saveexec_b64 s[20:21], s[4:5]
	s_cbranch_execz .LBB0_199
	s_waitcnt lgkmcnt(0)
	v_add_f32_e32 v17, v17, v30
	v_cndmask_b32_e64 v17, 0, v17, s[6:7]
	v_lshl_add_u64 v[30:31], s[38:39], 0, v[18:19]
	global_store_dword v[30:31], v17, off
	s_branch .LBB0_199
